# cmp_combine: w2 rows loaded 32 at a time, v_readlane broadcast + v_fmac instead of 128 serialized load+bpermute round trips per row
# speedup vs baseline: 1.0442x; 1.0155x over previous
.LBB0_597:
	s_ashr_i32 s10, s0, 12
	s_ashr_i32 s11, s10, 31
	s_and_b32 s12, s0, 0x1ff
	s_lshl_b64 s[8:9], s[10:11], 20
	s_add_u32 s8, s15, s8
	s_addc_u32 s9, s16, s9
	s_lshl_b32 s13, s0, 8
	s_and_b32 s17, s13, 0xfff00
	s_add_u32 s8, s8, s17
	s_addc_u32 s9, s9, 0
	s_cmpk_lg_i32 s12, 0x1ff
	s_mov_b64 s[12:13], -1
	s_cbranch_scc0 .LBB0_603
	s_lshl_b64 s[12:13], s[10:11], 24
	s_add_u32 s11, s1, s12
	s_addc_u32 s12, s14, s13
	s_lshl_b32 s13, s10, 7
	s_lshl_b32 s10, s17, 2
	v_add_u32_e32 v8, s13, v2
	s_add_u32 s10, s11, s10
	v_ashrrev_i32_e32 v9, 31, v8
	s_addc_u32 s11, s12, 0
	v_lshl_add_u64 v[8:9], v[8:9], 2, s[6:7]
	global_load_dword v23, v[8:9], off
	v_lshl_add_u64 v[8:9], v[2:3], 2, s[10:11]
	s_mov_b64 s[10:11], 0x400000
	v_lshl_add_u64 v[10:11], v[8:9], 0, s[10:11]
	s_mov_b32 s10, 0x400000
	v_add_co_u32_e32 v12, vcc, s10, v8
	s_mov_b64 s[10:11], 0x800000
	s_nop 0
	v_addc_co_u32_e32 v13, vcc, 0, v9, vcc
	global_load_dword v24, v[8:9], off
	global_load_dword v25, v[8:9], off offset:1536
	global_load_dword v26, v[12:13], off
	global_load_dword v27, v[10:11], off offset:1536
	v_lshl_add_u64 v[12:13], v[8:9], 0, s[10:11]
	s_mov_b32 s10, 0x800000
	v_add_co_u32_e32 v14, vcc, s10, v8
	s_mov_b64 s[10:11], 0xc00000
	s_nop 0
	v_addc_co_u32_e32 v15, vcc, 0, v9, vcc
	v_lshl_add_u64 v[20:21], v[8:9], 0, s[10:11]
	s_mov_b32 s10, 0xc00000
	v_add_co_u32_e32 v16, vcc, s10, v8
	s_cmpk_lt_u32 s0, 0x1000
	s_nop 0
	v_addc_co_u32_e32 v17, vcc, 0, v9, vcc
	global_load_dword v28, v[14:15], off
	global_load_dword v29, v[12:13], off offset:1536
	global_load_dword v30, v[16:17], off
	global_load_dword v31, v[20:21], off offset:1536
	v_add_u32_e32 v14, s13, v0
	v_ashrrev_i32_e32 v15, 31, v14
	v_lshl_add_u64 v[14:15], v[14:15], 2, s[6:7]
	global_load_dword v14, v[14:15], off
	s_nop 0
	global_load_dword v16, v[8:9], off offset:1792
	global_load_dword v15, v[10:11], off offset:1792
	global_load_dword v17, v[10:11], off offset:256
	global_load_dword v18, v[8:9], off offset:256
	global_load_dword v19, v[20:21], off offset:1792
	s_nop 0
	global_load_dword v20, v[20:21], off offset:256
	s_nop 0
	global_load_dword v21, v[12:13], off offset:1792
	global_load_dword v22, v[12:13], off offset:256
	v_mov_b32_e32 v12, 0
	s_cselect_b32 s11, s3, s5
	s_cselect_b32 s10, s2, s4
	s_mov_b32 s12, 0
	s_mov_b32 s13, 28
	s_waitcnt vmcnt(0) lgkmcnt(0)
	v_add_f32_e32 v8, v24, v25
	v_add_f32_e32 v8, v23, v8
	v_add_f32_e32 v9, v26, v27
	v_add_f32_e32 v8, v8, v9
	v_add_f32_e32 v10, v28, v29
	v_add_f32_e32 v8, v8, v10
	v_add_f32_e32 v11, v30, v31
	v_add_f32_e32 v13, v8, v11
	v_mul_f32_e32 v8, 0x3d372713, v13
	v_mul_f32_e32 v8, v13, v8
	v_fma_f32 v8, v13, v8, v13
	v_mul_f32_e32 v8, 0x3f4c422a, v8
	v_add_f32_e32 v8, v8, v8
	v_mul_f32_e32 v8, 0x3fb8aa3b, v8
	v_exp_f32_e32 v8, v8
	v_lshl_add_u64 v[10:11], s[10:11], 0, v[6:7]
	v_add_f32_e32 v8, 1.0, v8
	v_rcp_f32_e32 v23, v8
	v_lshl_add_u64 v[8:9], s[10:11], 0, v[4:5]
	v_sub_f32_e32 v23, 1.0, v23
	v_mul_f32_e32 v23, v13, v23
	v_mov_b32_e32 v13, v12
	v_mov_b64_e32 v[32:33], v[10:11]
	s_mov_b64 s[12:13], 0x1000
	global_load_dword v40, v[32:33], off
	global_load_dword v41, v[32:33], off offset:256
	global_load_dword v42, v[32:33], off offset:512
	global_load_dword v43, v[32:33], off offset:768
	global_load_dword v44, v[32:33], off offset:1024
	global_load_dword v45, v[32:33], off offset:1280
	global_load_dword v46, v[32:33], off offset:1536
	global_load_dword v47, v[32:33], off offset:1792
	global_load_dword v48, v[32:33], off offset:2048
	global_load_dword v49, v[32:33], off offset:2304
	global_load_dword v50, v[32:33], off offset:2560
	global_load_dword v51, v[32:33], off offset:2816
	global_load_dword v52, v[32:33], off offset:3072
	global_load_dword v53, v[32:33], off offset:3328
	global_load_dword v54, v[32:33], off offset:3584
	global_load_dword v55, v[32:33], off offset:3840
	v_lshl_add_u64 v[32:33], v[32:33], 0, s[12:13]
	global_load_dword v56, v[32:33], off
	global_load_dword v57, v[32:33], off offset:256
	global_load_dword v58, v[32:33], off offset:512
	global_load_dword v59, v[32:33], off offset:768
	global_load_dword v60, v[32:33], off offset:1024
	global_load_dword v61, v[32:33], off offset:1280
	global_load_dword v62, v[32:33], off offset:1536
	global_load_dword v63, v[32:33], off offset:1792
	global_load_dword v64, v[32:33], off offset:2048
	global_load_dword v65, v[32:33], off offset:2304
	global_load_dword v66, v[32:33], off offset:2560
	global_load_dword v67, v[32:33], off offset:2816
	global_load_dword v68, v[32:33], off offset:3072
	global_load_dword v69, v[32:33], off offset:3328
	global_load_dword v70, v[32:33], off offset:3584
	global_load_dword v71, v[32:33], off offset:3840
	v_lshl_add_u64 v[32:33], v[32:33], 0, s[12:13]
	global_load_dword v72, v[32:33], off
	global_load_dword v73, v[32:33], off offset:256
	global_load_dword v74, v[32:33], off offset:512
	global_load_dword v75, v[32:33], off offset:768
	global_load_dword v76, v[32:33], off offset:1024
	global_load_dword v77, v[32:33], off offset:1280
	global_load_dword v78, v[32:33], off offset:1536
	global_load_dword v79, v[32:33], off offset:1792
	global_load_dword v80, v[32:33], off offset:2048
	global_load_dword v81, v[32:33], off offset:2304
	global_load_dword v82, v[32:33], off offset:2560
	global_load_dword v83, v[32:33], off offset:2816
	global_load_dword v84, v[32:33], off offset:3072
	global_load_dword v85, v[32:33], off offset:3328
	global_load_dword v86, v[32:33], off offset:3584
	global_load_dword v87, v[32:33], off offset:3840
	v_lshl_add_u64 v[32:33], v[32:33], 0, s[12:13]
	global_load_dword v88, v[32:33], off
	global_load_dword v89, v[32:33], off offset:256
	global_load_dword v90, v[32:33], off offset:512
	global_load_dword v91, v[32:33], off offset:768
	global_load_dword v92, v[32:33], off offset:1024
	global_load_dword v93, v[32:33], off offset:1280
	global_load_dword v94, v[32:33], off offset:1536
	global_load_dword v95, v[32:33], off offset:1792
	global_load_dword v96, v[32:33], off offset:2048
	global_load_dword v97, v[32:33], off offset:2304
	global_load_dword v98, v[32:33], off offset:2560
	global_load_dword v99, v[32:33], off offset:2816
	global_load_dword v100, v[32:33], off offset:3072
	global_load_dword v101, v[32:33], off offset:3328
	global_load_dword v102, v[32:33], off offset:3584
	global_load_dword v103, v[32:33], off offset:3840
	v_lshl_add_u64 v[32:33], v[32:33], 0, s[12:13]
	s_waitcnt vmcnt(0)
	v_readlane_b32 s17, v23, 0
	v_readlane_b32 s20, v23, 1
	v_readlane_b32 s21, v23, 2
	v_fmac_f32_e32 v13, s17, v40
	v_fmac_f32_e32 v12, s17, v41
	v_readlane_b32 s17, v23, 3
	v_fmac_f32_e32 v13, s20, v42
	v_fmac_f32_e32 v12, s20, v43
	v_readlane_b32 s20, v23, 4
	v_fmac_f32_e32 v13, s21, v44
	v_fmac_f32_e32 v12, s21, v45
	v_readlane_b32 s21, v23, 5
	v_fmac_f32_e32 v13, s17, v46
	v_fmac_f32_e32 v12, s17, v47
	v_readlane_b32 s17, v23, 6
	v_fmac_f32_e32 v13, s20, v48
	v_fmac_f32_e32 v12, s20, v49
	v_readlane_b32 s20, v23, 7
	v_fmac_f32_e32 v13, s21, v50
	v_fmac_f32_e32 v12, s21, v51
	v_readlane_b32 s21, v23, 8
	v_fmac_f32_e32 v13, s17, v52
	v_fmac_f32_e32 v12, s17, v53
	v_readlane_b32 s17, v23, 9
	v_fmac_f32_e32 v13, s20, v54
	v_fmac_f32_e32 v12, s20, v55
	v_readlane_b32 s20, v23, 10
	v_fmac_f32_e32 v13, s21, v56
	v_fmac_f32_e32 v12, s21, v57
	v_readlane_b32 s21, v23, 11
	v_fmac_f32_e32 v13, s17, v58
	v_fmac_f32_e32 v12, s17, v59
	v_readlane_b32 s17, v23, 12
	v_fmac_f32_e32 v13, s20, v60
	v_fmac_f32_e32 v12, s20, v61
	v_readlane_b32 s20, v23, 13
	v_fmac_f32_e32 v13, s21, v62
	v_fmac_f32_e32 v12, s21, v63
	v_readlane_b32 s21, v23, 14
	v_fmac_f32_e32 v13, s17, v64
	v_fmac_f32_e32 v12, s17, v65
	v_readlane_b32 s17, v23, 15
	v_fmac_f32_e32 v13, s20, v66
	v_fmac_f32_e32 v12, s20, v67
	v_readlane_b32 s20, v23, 16
	v_fmac_f32_e32 v13, s21, v68
	v_fmac_f32_e32 v12, s21, v69
	v_readlane_b32 s21, v23, 17
	v_fmac_f32_e32 v13, s17, v70
	v_fmac_f32_e32 v12, s17, v71
	v_readlane_b32 s17, v23, 18
	v_fmac_f32_e32 v13, s20, v72
	v_fmac_f32_e32 v12, s20, v73
	v_readlane_b32 s20, v23, 19
	v_fmac_f32_e32 v13, s21, v74
	v_fmac_f32_e32 v12, s21, v75
	v_readlane_b32 s21, v23, 20
	v_fmac_f32_e32 v13, s17, v76
	v_fmac_f32_e32 v12, s17, v77
	v_readlane_b32 s17, v23, 21
	v_fmac_f32_e32 v13, s20, v78
	v_fmac_f32_e32 v12, s20, v79
	v_readlane_b32 s20, v23, 22
	v_fmac_f32_e32 v13, s21, v80
	v_fmac_f32_e32 v12, s21, v81
	v_readlane_b32 s21, v23, 23
	v_fmac_f32_e32 v13, s17, v82
	v_fmac_f32_e32 v12, s17, v83
	v_readlane_b32 s17, v23, 24
	v_fmac_f32_e32 v13, s20, v84
	v_fmac_f32_e32 v12, s20, v85
	v_readlane_b32 s20, v23, 25
	v_fmac_f32_e32 v13, s21, v86
	v_fmac_f32_e32 v12, s21, v87
	v_readlane_b32 s21, v23, 26
	v_fmac_f32_e32 v13, s17, v88
	v_fmac_f32_e32 v12, s17, v89
	v_readlane_b32 s17, v23, 27
	v_fmac_f32_e32 v13, s20, v90
	v_fmac_f32_e32 v12, s20, v91
	v_readlane_b32 s20, v23, 28
	v_fmac_f32_e32 v13, s21, v92
	v_fmac_f32_e32 v12, s21, v93
	v_readlane_b32 s21, v23, 29
	v_fmac_f32_e32 v13, s17, v94
	v_fmac_f32_e32 v12, s17, v95
	v_readlane_b32 s17, v23, 30
	v_fmac_f32_e32 v13, s20, v96
	v_fmac_f32_e32 v12, s20, v97
	v_readlane_b32 s20, v23, 31
	v_fmac_f32_e32 v13, s21, v98
	v_fmac_f32_e32 v12, s21, v99
	v_fmac_f32_e32 v13, s17, v100
	v_fmac_f32_e32 v12, s17, v101
	v_fmac_f32_e32 v13, s20, v102
	v_fmac_f32_e32 v12, s20, v103
	global_load_dword v40, v[32:33], off
	global_load_dword v41, v[32:33], off offset:256
	global_load_dword v42, v[32:33], off offset:512
	global_load_dword v43, v[32:33], off offset:768
	global_load_dword v44, v[32:33], off offset:1024
	global_load_dword v45, v[32:33], off offset:1280
	global_load_dword v46, v[32:33], off offset:1536
	global_load_dword v47, v[32:33], off offset:1792
	global_load_dword v48, v[32:33], off offset:2048
	global_load_dword v49, v[32:33], off offset:2304
	global_load_dword v50, v[32:33], off offset:2560
	global_load_dword v51, v[32:33], off offset:2816
	global_load_dword v52, v[32:33], off offset:3072
	global_load_dword v53, v[32:33], off offset:3328
	global_load_dword v54, v[32:33], off offset:3584
	global_load_dword v55, v[32:33], off offset:3840
	v_lshl_add_u64 v[32:33], v[32:33], 0, s[12:13]
	global_load_dword v56, v[32:33], off
	global_load_dword v57, v[32:33], off offset:256
	global_load_dword v58, v[32:33], off offset:512
	global_load_dword v59, v[32:33], off offset:768
	global_load_dword v60, v[32:33], off offset:1024
	global_load_dword v61, v[32:33], off offset:1280
	global_load_dword v62, v[32:33], off offset:1536
	global_load_dword v63, v[32:33], off offset:1792
	global_load_dword v64, v[32:33], off offset:2048
	global_load_dword v65, v[32:33], off offset:2304
	global_load_dword v66, v[32:33], off offset:2560
	global_load_dword v67, v[32:33], off offset:2816
	global_load_dword v68, v[32:33], off offset:3072
	global_load_dword v69, v[32:33], off offset:3328
	global_load_dword v70, v[32:33], off offset:3584
	global_load_dword v71, v[32:33], off offset:3840
	v_lshl_add_u64 v[32:33], v[32:33], 0, s[12:13]
	global_load_dword v72, v[32:33], off
	global_load_dword v73, v[32:33], off offset:256
	global_load_dword v74, v[32:33], off offset:512
	global_load_dword v75, v[32:33], off offset:768
	global_load_dword v76, v[32:33], off offset:1024
	global_load_dword v77, v[32:33], off offset:1280
	global_load_dword v78, v[32:33], off offset:1536
	global_load_dword v79, v[32:33], off offset:1792
	global_load_dword v80, v[32:33], off offset:2048
	global_load_dword v81, v[32:33], off offset:2304
	global_load_dword v82, v[32:33], off offset:2560
	global_load_dword v83, v[32:33], off offset:2816
	global_load_dword v84, v[32:33], off offset:3072
	global_load_dword v85, v[32:33], off offset:3328
	global_load_dword v86, v[32:33], off offset:3584
	global_load_dword v87, v[32:33], off offset:3840
	v_lshl_add_u64 v[32:33], v[32:33], 0, s[12:13]
	global_load_dword v88, v[32:33], off
	global_load_dword v89, v[32:33], off offset:256
	global_load_dword v90, v[32:33], off offset:512
	global_load_dword v91, v[32:33], off offset:768
	global_load_dword v92, v[32:33], off offset:1024
	global_load_dword v93, v[32:33], off offset:1280
	global_load_dword v94, v[32:33], off offset:1536
	global_load_dword v95, v[32:33], off offset:1792
	global_load_dword v96, v[32:33], off offset:2048
	global_load_dword v97, v[32:33], off offset:2304
	global_load_dword v98, v[32:33], off offset:2560
	global_load_dword v99, v[32:33], off offset:2816
	global_load_dword v100, v[32:33], off offset:3072
	global_load_dword v101, v[32:33], off offset:3328
	global_load_dword v102, v[32:33], off offset:3584
	global_load_dword v103, v[32:33], off offset:3840
	v_lshl_add_u64 v[32:33], v[32:33], 0, s[12:13]
	s_waitcnt vmcnt(0)
	v_readlane_b32 s17, v23, 32
	v_readlane_b32 s20, v23, 33
	v_readlane_b32 s21, v23, 34
	v_fmac_f32_e32 v13, s17, v40
	v_fmac_f32_e32 v12, s17, v41
	v_readlane_b32 s17, v23, 35
	v_fmac_f32_e32 v13, s20, v42
	v_fmac_f32_e32 v12, s20, v43
	v_readlane_b32 s20, v23, 36
	v_fmac_f32_e32 v13, s21, v44
	v_fmac_f32_e32 v12, s21, v45
	v_readlane_b32 s21, v23, 37
	v_fmac_f32_e32 v13, s17, v46
	v_fmac_f32_e32 v12, s17, v47
	v_readlane_b32 s17, v23, 38
	v_fmac_f32_e32 v13, s20, v48
	v_fmac_f32_e32 v12, s20, v49
	v_readlane_b32 s20, v23, 39
	v_fmac_f32_e32 v13, s21, v50
	v_fmac_f32_e32 v12, s21, v51
	v_readlane_b32 s21, v23, 40
	v_fmac_f32_e32 v13, s17, v52
	v_fmac_f32_e32 v12, s17, v53
	v_readlane_b32 s17, v23, 41
	v_fmac_f32_e32 v13, s20, v54
	v_fmac_f32_e32 v12, s20, v55
	v_readlane_b32 s20, v23, 42
	v_fmac_f32_e32 v13, s21, v56
	v_fmac_f32_e32 v12, s21, v57
	v_readlane_b32 s21, v23, 43
	v_fmac_f32_e32 v13, s17, v58
	v_fmac_f32_e32 v12, s17, v59
	v_readlane_b32 s17, v23, 44
	v_fmac_f32_e32 v13, s20, v60
	v_fmac_f32_e32 v12, s20, v61
	v_readlane_b32 s20, v23, 45
	v_fmac_f32_e32 v13, s21, v62
	v_fmac_f32_e32 v12, s21, v63
	v_readlane_b32 s21, v23, 46
	v_fmac_f32_e32 v13, s17, v64
	v_fmac_f32_e32 v12, s17, v65
	v_readlane_b32 s17, v23, 47
	v_fmac_f32_e32 v13, s20, v66
	v_fmac_f32_e32 v12, s20, v67
	v_readlane_b32 s20, v23, 48
	v_fmac_f32_e32 v13, s21, v68
	v_fmac_f32_e32 v12, s21, v69
	v_readlane_b32 s21, v23, 49
	v_fmac_f32_e32 v13, s17, v70
	v_fmac_f32_e32 v12, s17, v71
	v_readlane_b32 s17, v23, 50
	v_fmac_f32_e32 v13, s20, v72
	v_fmac_f32_e32 v12, s20, v73
	v_readlane_b32 s20, v23, 51
	v_fmac_f32_e32 v13, s21, v74
	v_fmac_f32_e32 v12, s21, v75
	v_readlane_b32 s21, v23, 52
	v_fmac_f32_e32 v13, s17, v76
	v_fmac_f32_e32 v12, s17, v77
	v_readlane_b32 s17, v23, 53
	v_fmac_f32_e32 v13, s20, v78
	v_fmac_f32_e32 v12, s20, v79
	v_readlane_b32 s20, v23, 54
	v_fmac_f32_e32 v13, s21, v80
	v_fmac_f32_e32 v12, s21, v81
	v_readlane_b32 s21, v23, 55
	v_fmac_f32_e32 v13, s17, v82
	v_fmac_f32_e32 v12, s17, v83
	v_readlane_b32 s17, v23, 56
	v_fmac_f32_e32 v13, s20, v84
	v_fmac_f32_e32 v12, s20, v85
	v_readlane_b32 s20, v23, 57
	v_fmac_f32_e32 v13, s21, v86
	v_fmac_f32_e32 v12, s21, v87
	v_readlane_b32 s21, v23, 58
	v_fmac_f32_e32 v13, s17, v88
	v_fmac_f32_e32 v12, s17, v89
	v_readlane_b32 s17, v23, 59
	v_fmac_f32_e32 v13, s20, v90
	v_fmac_f32_e32 v12, s20, v91
	v_readlane_b32 s20, v23, 60
	v_fmac_f32_e32 v13, s21, v92
	v_fmac_f32_e32 v12, s21, v93
	v_readlane_b32 s21, v23, 61
	v_fmac_f32_e32 v13, s17, v94
	v_fmac_f32_e32 v12, s17, v95
	v_readlane_b32 s17, v23, 62
	v_fmac_f32_e32 v13, s20, v96
	v_fmac_f32_e32 v12, s20, v97
	v_readlane_b32 s20, v23, 63
	v_fmac_f32_e32 v13, s21, v98
	v_fmac_f32_e32 v12, s21, v99
	v_fmac_f32_e32 v13, s17, v100
	v_fmac_f32_e32 v12, s17, v101
	v_fmac_f32_e32 v13, s20, v102
	v_fmac_f32_e32 v12, s20, v103
	v_add_f32_e32 v8, v18, v16
	v_add_f32_e32 v8, v14, v8
	v_add_f32_e32 v9, v17, v15
	v_add_f32_e32 v8, v8, v9
	v_add_f32_e32 v9, v22, v21
	v_add_f32_e32 v8, v8, v9
	v_add_f32_e32 v9, v20, v19
	v_add_f32_e32 v8, v8, v9
	v_mul_f32_e32 v9, 0x3d372713, v8
	v_mul_f32_e32 v9, v8, v9
	v_fma_f32 v9, v8, v9, v8
	v_mul_f32_e32 v9, 0x3f4c422a, v9
	v_add_f32_e32 v9, v9, v9
	v_mul_f32_e32 v9, 0x3fb8aa3b, v9
	v_exp_f32_e32 v9, v9
	s_mov_b32 s12, 28
	s_mov_b32 s13, 0
	v_add_f32_e32 v9, 1.0, v9
	v_rcp_f32_e32 v9, v9
	s_nop 0
	v_sub_f32_e32 v9, 1.0, v9
	v_mul_f32_e32 v8, v8, v9
	s_mov_b64 s[12:13], 0x1000
	global_load_dword v40, v[32:33], off
	global_load_dword v41, v[32:33], off offset:256
	global_load_dword v42, v[32:33], off offset:512
	global_load_dword v43, v[32:33], off offset:768
	global_load_dword v44, v[32:33], off offset:1024
	global_load_dword v45, v[32:33], off offset:1280
	global_load_dword v46, v[32:33], off offset:1536
	global_load_dword v47, v[32:33], off offset:1792
	global_load_dword v48, v[32:33], off offset:2048
	global_load_dword v49, v[32:33], off offset:2304
	global_load_dword v50, v[32:33], off offset:2560
	global_load_dword v51, v[32:33], off offset:2816
	global_load_dword v52, v[32:33], off offset:3072
	global_load_dword v53, v[32:33], off offset:3328
	global_load_dword v54, v[32:33], off offset:3584
	global_load_dword v55, v[32:33], off offset:3840
	v_lshl_add_u64 v[32:33], v[32:33], 0, s[12:13]
	global_load_dword v56, v[32:33], off
	global_load_dword v57, v[32:33], off offset:256
	global_load_dword v58, v[32:33], off offset:512
	global_load_dword v59, v[32:33], off offset:768
	global_load_dword v60, v[32:33], off offset:1024
	global_load_dword v61, v[32:33], off offset:1280
	global_load_dword v62, v[32:33], off offset:1536
	global_load_dword v63, v[32:33], off offset:1792
	global_load_dword v64, v[32:33], off offset:2048
	global_load_dword v65, v[32:33], off offset:2304
	global_load_dword v66, v[32:33], off offset:2560
	global_load_dword v67, v[32:33], off offset:2816
	global_load_dword v68, v[32:33], off offset:3072
	global_load_dword v69, v[32:33], off offset:3328
	global_load_dword v70, v[32:33], off offset:3584
	global_load_dword v71, v[32:33], off offset:3840
	v_lshl_add_u64 v[32:33], v[32:33], 0, s[12:13]
	global_load_dword v72, v[32:33], off
	global_load_dword v73, v[32:33], off offset:256
	global_load_dword v74, v[32:33], off offset:512
	global_load_dword v75, v[32:33], off offset:768
	global_load_dword v76, v[32:33], off offset:1024
	global_load_dword v77, v[32:33], off offset:1280
	global_load_dword v78, v[32:33], off offset:1536
	global_load_dword v79, v[32:33], off offset:1792
	global_load_dword v80, v[32:33], off offset:2048
	global_load_dword v81, v[32:33], off offset:2304
	global_load_dword v82, v[32:33], off offset:2560
	global_load_dword v83, v[32:33], off offset:2816
	global_load_dword v84, v[32:33], off offset:3072
	global_load_dword v85, v[32:33], off offset:3328
	global_load_dword v86, v[32:33], off offset:3584
	global_load_dword v87, v[32:33], off offset:3840
	v_lshl_add_u64 v[32:33], v[32:33], 0, s[12:13]
	global_load_dword v88, v[32:33], off
	global_load_dword v89, v[32:33], off offset:256
	global_load_dword v90, v[32:33], off offset:512
	global_load_dword v91, v[32:33], off offset:768
	global_load_dword v92, v[32:33], off offset:1024
	global_load_dword v93, v[32:33], off offset:1280
	global_load_dword v94, v[32:33], off offset:1536
	global_load_dword v95, v[32:33], off offset:1792
	global_load_dword v96, v[32:33], off offset:2048
	global_load_dword v97, v[32:33], off offset:2304
	global_load_dword v98, v[32:33], off offset:2560
	global_load_dword v99, v[32:33], off offset:2816
	global_load_dword v100, v[32:33], off offset:3072
	global_load_dword v101, v[32:33], off offset:3328
	global_load_dword v102, v[32:33], off offset:3584
	global_load_dword v103, v[32:33], off offset:3840
	v_lshl_add_u64 v[32:33], v[32:33], 0, s[12:13]
	s_waitcnt vmcnt(0)
	v_readlane_b32 s17, v8, 0
	v_readlane_b32 s20, v8, 1
	v_readlane_b32 s21, v8, 2
	v_fmac_f32_e32 v13, s17, v40
	v_fmac_f32_e32 v12, s17, v41
	v_readlane_b32 s17, v8, 3
	v_fmac_f32_e32 v13, s20, v42
	v_fmac_f32_e32 v12, s20, v43
	v_readlane_b32 s20, v8, 4
	v_fmac_f32_e32 v13, s21, v44
	v_fmac_f32_e32 v12, s21, v45
	v_readlane_b32 s21, v8, 5
	v_fmac_f32_e32 v13, s17, v46
	v_fmac_f32_e32 v12, s17, v47
	v_readlane_b32 s17, v8, 6
	v_fmac_f32_e32 v13, s20, v48
	v_fmac_f32_e32 v12, s20, v49
	v_readlane_b32 s20, v8, 7
	v_fmac_f32_e32 v13, s21, v50
	v_fmac_f32_e32 v12, s21, v51
	v_readlane_b32 s21, v8, 8
	v_fmac_f32_e32 v13, s17, v52
	v_fmac_f32_e32 v12, s17, v53
	v_readlane_b32 s17, v8, 9
	v_fmac_f32_e32 v13, s20, v54
	v_fmac_f32_e32 v12, s20, v55
	v_readlane_b32 s20, v8, 10
	v_fmac_f32_e32 v13, s21, v56
	v_fmac_f32_e32 v12, s21, v57
	v_readlane_b32 s21, v8, 11
	v_fmac_f32_e32 v13, s17, v58
	v_fmac_f32_e32 v12, s17, v59
	v_readlane_b32 s17, v8, 12
	v_fmac_f32_e32 v13, s20, v60
	v_fmac_f32_e32 v12, s20, v61
	v_readlane_b32 s20, v8, 13
	v_fmac_f32_e32 v13, s21, v62
	v_fmac_f32_e32 v12, s21, v63
	v_readlane_b32 s21, v8, 14
	v_fmac_f32_e32 v13, s17, v64
	v_fmac_f32_e32 v12, s17, v65
	v_readlane_b32 s17, v8, 15
	v_fmac_f32_e32 v13, s20, v66
	v_fmac_f32_e32 v12, s20, v67
	v_readlane_b32 s20, v8, 16
	v_fmac_f32_e32 v13, s21, v68
	v_fmac_f32_e32 v12, s21, v69
	v_readlane_b32 s21, v8, 17
	v_fmac_f32_e32 v13, s17, v70
	v_fmac_f32_e32 v12, s17, v71
	v_readlane_b32 s17, v8, 18
	v_fmac_f32_e32 v13, s20, v72
	v_fmac_f32_e32 v12, s20, v73
	v_readlane_b32 s20, v8, 19
	v_fmac_f32_e32 v13, s21, v74
	v_fmac_f32_e32 v12, s21, v75
	v_readlane_b32 s21, v8, 20
	v_fmac_f32_e32 v13, s17, v76
	v_fmac_f32_e32 v12, s17, v77
	v_readlane_b32 s17, v8, 21
	v_fmac_f32_e32 v13, s20, v78
	v_fmac_f32_e32 v12, s20, v79
	v_readlane_b32 s20, v8, 22
	v_fmac_f32_e32 v13, s21, v80
	v_fmac_f32_e32 v12, s21, v81
	v_readlane_b32 s21, v8, 23
	v_fmac_f32_e32 v13, s17, v82
	v_fmac_f32_e32 v12, s17, v83
	v_readlane_b32 s17, v8, 24
	v_fmac_f32_e32 v13, s20, v84
	v_fmac_f32_e32 v12, s20, v85
	v_readlane_b32 s20, v8, 25
	v_fmac_f32_e32 v13, s21, v86
	v_fmac_f32_e32 v12, s21, v87
	v_readlane_b32 s21, v8, 26
	v_fmac_f32_e32 v13, s17, v88
	v_fmac_f32_e32 v12, s17, v89
	v_readlane_b32 s17, v8, 27
	v_fmac_f32_e32 v13, s20, v90
	v_fmac_f32_e32 v12, s20, v91
	v_readlane_b32 s20, v8, 28
	v_fmac_f32_e32 v13, s21, v92
	v_fmac_f32_e32 v12, s21, v93
	v_readlane_b32 s21, v8, 29
	v_fmac_f32_e32 v13, s17, v94
	v_fmac_f32_e32 v12, s17, v95
	v_readlane_b32 s17, v8, 30
	v_fmac_f32_e32 v13, s20, v96
	v_fmac_f32_e32 v12, s20, v97
	v_readlane_b32 s20, v8, 31
	v_fmac_f32_e32 v13, s21, v98
	v_fmac_f32_e32 v12, s21, v99
	v_fmac_f32_e32 v13, s17, v100
	v_fmac_f32_e32 v12, s17, v101
	v_fmac_f32_e32 v13, s20, v102
	v_fmac_f32_e32 v12, s20, v103
	global_load_dword v40, v[32:33], off
	global_load_dword v41, v[32:33], off offset:256
	global_load_dword v42, v[32:33], off offset:512
	global_load_dword v43, v[32:33], off offset:768
	global_load_dword v44, v[32:33], off offset:1024
	global_load_dword v45, v[32:33], off offset:1280
	global_load_dword v46, v[32:33], off offset:1536
	global_load_dword v47, v[32:33], off offset:1792
	global_load_dword v48, v[32:33], off offset:2048
	global_load_dword v49, v[32:33], off offset:2304
	global_load_dword v50, v[32:33], off offset:2560
	global_load_dword v51, v[32:33], off offset:2816
	global_load_dword v52, v[32:33], off offset:3072
	global_load_dword v53, v[32:33], off offset:3328
	global_load_dword v54, v[32:33], off offset:3584
	global_load_dword v55, v[32:33], off offset:3840
	v_lshl_add_u64 v[32:33], v[32:33], 0, s[12:13]
	global_load_dword v56, v[32:33], off
	global_load_dword v57, v[32:33], off offset:256
	global_load_dword v58, v[32:33], off offset:512
	global_load_dword v59, v[32:33], off offset:768
	global_load_dword v60, v[32:33], off offset:1024
	global_load_dword v61, v[32:33], off offset:1280
	global_load_dword v62, v[32:33], off offset:1536
	global_load_dword v63, v[32:33], off offset:1792
	global_load_dword v64, v[32:33], off offset:2048
	global_load_dword v65, v[32:33], off offset:2304
	global_load_dword v66, v[32:33], off offset:2560
	global_load_dword v67, v[32:33], off offset:2816
	global_load_dword v68, v[32:33], off offset:3072
	global_load_dword v69, v[32:33], off offset:3328
	global_load_dword v70, v[32:33], off offset:3584
	global_load_dword v71, v[32:33], off offset:3840
	v_lshl_add_u64 v[32:33], v[32:33], 0, s[12:13]
	global_load_dword v72, v[32:33], off
	global_load_dword v73, v[32:33], off offset:256
	global_load_dword v74, v[32:33], off offset:512
	global_load_dword v75, v[32:33], off offset:768
	global_load_dword v76, v[32:33], off offset:1024
	global_load_dword v77, v[32:33], off offset:1280
	global_load_dword v78, v[32:33], off offset:1536
	global_load_dword v79, v[32:33], off offset:1792
	global_load_dword v80, v[32:33], off offset:2048
	global_load_dword v81, v[32:33], off offset:2304
	global_load_dword v82, v[32:33], off offset:2560
	global_load_dword v83, v[32:33], off offset:2816
	global_load_dword v84, v[32:33], off offset:3072
	global_load_dword v85, v[32:33], off offset:3328
	global_load_dword v86, v[32:33], off offset:3584
	global_load_dword v87, v[32:33], off offset:3840
	v_lshl_add_u64 v[32:33], v[32:33], 0, s[12:13]
	global_load_dword v88, v[32:33], off
	global_load_dword v89, v[32:33], off offset:256
	global_load_dword v90, v[32:33], off offset:512
	global_load_dword v91, v[32:33], off offset:768
	global_load_dword v92, v[32:33], off offset:1024
	global_load_dword v93, v[32:33], off offset:1280
	global_load_dword v94, v[32:33], off offset:1536
	global_load_dword v95, v[32:33], off offset:1792
	global_load_dword v96, v[32:33], off offset:2048
	global_load_dword v97, v[32:33], off offset:2304
	global_load_dword v98, v[32:33], off offset:2560
	global_load_dword v99, v[32:33], off offset:2816
	global_load_dword v100, v[32:33], off offset:3072
	global_load_dword v101, v[32:33], off offset:3328
	global_load_dword v102, v[32:33], off offset:3584
	global_load_dword v103, v[32:33], off offset:3840
	v_lshl_add_u64 v[32:33], v[32:33], 0, s[12:13]
	s_waitcnt vmcnt(0)
	v_readlane_b32 s17, v8, 32
	v_readlane_b32 s20, v8, 33
	v_readlane_b32 s21, v8, 34
	v_fmac_f32_e32 v13, s17, v40
	v_fmac_f32_e32 v12, s17, v41
	v_readlane_b32 s17, v8, 35
	v_fmac_f32_e32 v13, s20, v42
	v_fmac_f32_e32 v12, s20, v43
	v_readlane_b32 s20, v8, 36
	v_fmac_f32_e32 v13, s21, v44
	v_fmac_f32_e32 v12, s21, v45
	v_readlane_b32 s21, v8, 37
	v_fmac_f32_e32 v13, s17, v46
	v_fmac_f32_e32 v12, s17, v47
	v_readlane_b32 s17, v8, 38
	v_fmac_f32_e32 v13, s20, v48
	v_fmac_f32_e32 v12, s20, v49
	v_readlane_b32 s20, v8, 39
	v_fmac_f32_e32 v13, s21, v50
	v_fmac_f32_e32 v12, s21, v51
	v_readlane_b32 s21, v8, 40
	v_fmac_f32_e32 v13, s17, v52
	v_fmac_f32_e32 v12, s17, v53
	v_readlane_b32 s17, v8, 41
	v_fmac_f32_e32 v13, s20, v54
	v_fmac_f32_e32 v12, s20, v55
	v_readlane_b32 s20, v8, 42
	v_fmac_f32_e32 v13, s21, v56
	v_fmac_f32_e32 v12, s21, v57
	v_readlane_b32 s21, v8, 43
	v_fmac_f32_e32 v13, s17, v58
	v_fmac_f32_e32 v12, s17, v59
	v_readlane_b32 s17, v8, 44
	v_fmac_f32_e32 v13, s20, v60
	v_fmac_f32_e32 v12, s20, v61
	v_readlane_b32 s20, v8, 45
	v_fmac_f32_e32 v13, s21, v62
	v_fmac_f32_e32 v12, s21, v63
	v_readlane_b32 s21, v8, 46
	v_fmac_f32_e32 v13, s17, v64
	v_fmac_f32_e32 v12, s17, v65
	v_readlane_b32 s17, v8, 47
	v_fmac_f32_e32 v13, s20, v66
	v_fmac_f32_e32 v12, s20, v67
	v_readlane_b32 s20, v8, 48
	v_fmac_f32_e32 v13, s21, v68
	v_fmac_f32_e32 v12, s21, v69
	v_readlane_b32 s21, v8, 49
	v_fmac_f32_e32 v13, s17, v70
	v_fmac_f32_e32 v12, s17, v71
	v_readlane_b32 s17, v8, 50
	v_fmac_f32_e32 v13, s20, v72
	v_fmac_f32_e32 v12, s20, v73
	v_readlane_b32 s20, v8, 51
	v_fmac_f32_e32 v13, s21, v74
	v_fmac_f32_e32 v12, s21, v75
	v_readlane_b32 s21, v8, 52
	v_fmac_f32_e32 v13, s17, v76
	v_fmac_f32_e32 v12, s17, v77
	v_readlane_b32 s17, v8, 53
	v_fmac_f32_e32 v13, s20, v78
	v_fmac_f32_e32 v12, s20, v79
	v_readlane_b32 s20, v8, 54
	v_fmac_f32_e32 v13, s21, v80
	v_fmac_f32_e32 v12, s21, v81
	v_readlane_b32 s21, v8, 55
	v_fmac_f32_e32 v13, s17, v82
	v_fmac_f32_e32 v12, s17, v83
	v_readlane_b32 s17, v8, 56
	v_fmac_f32_e32 v13, s20, v84
	v_fmac_f32_e32 v12, s20, v85
	v_readlane_b32 s20, v8, 57
	v_fmac_f32_e32 v13, s21, v86
	v_fmac_f32_e32 v12, s21, v87
	v_readlane_b32 s21, v8, 58
	v_fmac_f32_e32 v13, s17, v88
	v_fmac_f32_e32 v12, s17, v89
	v_readlane_b32 s17, v8, 59
	v_fmac_f32_e32 v13, s20, v90
	v_fmac_f32_e32 v12, s20, v91
	v_readlane_b32 s20, v8, 60
	v_fmac_f32_e32 v13, s21, v92
	v_fmac_f32_e32 v12, s21, v93
	v_readlane_b32 s21, v8, 61
	v_fmac_f32_e32 v13, s17, v94
	v_fmac_f32_e32 v12, s17, v95
	v_readlane_b32 s17, v8, 62
	v_fmac_f32_e32 v13, s20, v96
	v_fmac_f32_e32 v12, s20, v97
	v_readlane_b32 s20, v8, 63
	v_fmac_f32_e32 v13, s21, v98
	v_fmac_f32_e32 v12, s21, v99
	v_fmac_f32_e32 v13, s17, v100
	v_fmac_f32_e32 v12, s17, v101
	v_fmac_f32_e32 v13, s20, v102
	v_fmac_f32_e32 v12, s20, v103
	v_bfe_u32 v8, v13, 16, 1
	v_add3_u32 v10, v13, v8, s97
	v_lshl_add_u64 v[8:9], v[2:3], 1, s[8:9]
	global_store_short_d16_hi v[8:9], v10, off
	v_bfe_u32 v8, v12, 16, 1
	v_add3_u32 v8, v12, v8, s97
	v_lshrrev_b32_e32 v10, 16, v8
	v_lshl_add_u64 v[8:9], v[2:3], 1, s[8:9]
	s_branch .LBB0_596
